# attention exp block and PV MFMAs interleaved group by group (in-place exp and bf16 pack), with static priority and packed SwiGLU epilogue
# baseline (speedup 1.0000x reference)
.LBB0_319:
	v_or_b32_e32 v221, s31, v202
	v_mad_u32_u24 v225, v221, s89, v206
	ds_read_b64_tr_b16 v[226:227], v225 offset:18432
	ds_read_b64_tr_b16 v[228:229], v225 offset:19584
	ds_read_b64_tr_b16 v[230:231], v225 offset:18496
	ds_read_b64_tr_b16 v[232:233], v225 offset:19648
	ds_read_b64_tr_b16 v[234:235], v225 offset:20736
	ds_read_b64_tr_b16 v[236:237], v225 offset:21888
	v_pk_add_f32 v[114:115], v[114:115], v[186:187] op_sel_hi:[1,0] neg_lo:[0,1] neg_hi:[0,1]
	v_pk_add_f32 v[116:117], v[116:117], v[186:187] op_sel_hi:[1,0] neg_lo:[0,1] neg_hi:[0,1]
	v_pk_add_f32 v[118:119], v[118:119], v[186:187] op_sel_hi:[1,0] neg_lo:[0,1] neg_hi:[0,1]
	v_pk_add_f32 v[120:121], v[120:121], v[186:187] op_sel_hi:[1,0] neg_lo:[0,1] neg_hi:[0,1]
	v_exp_f32_e32 v114, v114
	v_exp_f32_e32 v115, v115
	v_exp_f32_e32 v116, v116
	v_exp_f32_e32 v117, v117
	v_exp_f32_e32 v118, v118
	v_exp_f32_e32 v119, v119
	v_exp_f32_e32 v120, v120
	v_exp_f32_e32 v121, v121
	v_pk_add_f32 v[220:221], v[114:115], v[116:117]
	v_pk_add_f32 v[220:221], v[220:221], v[118:119]
	v_pk_add_f32 v[220:221], v[220:221], v[120:121]
	v_add_f32_e32 v220, v220, v221
	v_add_f32_e32 v201, v201, v220
	v_cvt_pk_bf16_f32 v114, v114, v115
	v_cvt_pk_bf16_f32 v115, v116, v117
	v_cvt_pk_bf16_f32 v116, v118, v119
	v_cvt_pk_bf16_f32 v117, v120, v121
	v_pk_add_f32 v[82:83], v[82:83], v[188:189] op_sel_hi:[1,0] neg_lo:[0,1] neg_hi:[0,1]
	v_pk_add_f32 v[84:85], v[84:85], v[188:189] op_sel_hi:[1,0] neg_lo:[0,1] neg_hi:[0,1]
	v_pk_add_f32 v[86:87], v[86:87], v[188:189] op_sel_hi:[1,0] neg_lo:[0,1] neg_hi:[0,1]
	v_pk_add_f32 v[88:89], v[88:89], v[188:189] op_sel_hi:[1,0] neg_lo:[0,1] neg_hi:[0,1]
	v_exp_f32_e32 v82, v82
	v_exp_f32_e32 v83, v83
	v_exp_f32_e32 v84, v84
	v_exp_f32_e32 v85, v85
	v_exp_f32_e32 v86, v86
	v_exp_f32_e32 v87, v87
	v_exp_f32_e32 v88, v88
	v_exp_f32_e32 v89, v89
	v_pk_add_f32 v[220:221], v[82:83], v[84:85]
	v_pk_add_f32 v[220:221], v[220:221], v[86:87]
	v_pk_add_f32 v[220:221], v[220:221], v[88:89]
	v_add_f32_e32 v220, v220, v221
	v_add_f32_e32 v199, v199, v220
	v_cvt_pk_bf16_f32 v82, v82, v83
	v_cvt_pk_bf16_f32 v83, v84, v85
	v_cvt_pk_bf16_f32 v84, v86, v87
	v_cvt_pk_bf16_f32 v85, v88, v89
	s_waitcnt lgkmcnt(4)
	v_mfma_f32_32x32x16_bf16 v[50:65], v[226:229], v[114:117], v[50:65]
	v_mfma_f32_32x32x16_bf16 v[18:33], v[226:229], v[82:85], v[18:33]
	ds_read_b64_tr_b16 v[226:227], v225 offset:20800
	ds_read_b64_tr_b16 v[228:229], v225 offset:21952
	v_pk_add_f32 v[122:123], v[122:123], v[186:187] op_sel_hi:[1,0] neg_lo:[0,1] neg_hi:[0,1]
	v_pk_add_f32 v[124:125], v[124:125], v[186:187] op_sel_hi:[1,0] neg_lo:[0,1] neg_hi:[0,1]
	v_pk_add_f32 v[126:127], v[126:127], v[186:187] op_sel_hi:[1,0] neg_lo:[0,1] neg_hi:[0,1]
	v_pk_add_f32 v[128:129], v[128:129], v[186:187] op_sel_hi:[1,0] neg_lo:[0,1] neg_hi:[0,1]
	v_exp_f32_e32 v122, v122
	v_exp_f32_e32 v123, v123
	v_exp_f32_e32 v124, v124
	v_exp_f32_e32 v125, v125
	v_exp_f32_e32 v126, v126
	v_exp_f32_e32 v127, v127
	v_exp_f32_e32 v128, v128
	v_exp_f32_e32 v129, v129
	v_pk_add_f32 v[220:221], v[122:123], v[124:125]
	v_pk_add_f32 v[220:221], v[220:221], v[126:127]
	v_pk_add_f32 v[220:221], v[220:221], v[128:129]
	v_add_f32_e32 v220, v220, v221
	v_add_f32_e32 v201, v201, v220
	v_cvt_pk_bf16_f32 v122, v122, v123
	v_cvt_pk_bf16_f32 v123, v124, v125
	v_cvt_pk_bf16_f32 v124, v126, v127
	v_cvt_pk_bf16_f32 v125, v128, v129
	s_waitcnt lgkmcnt(4)
	v_mfma_f32_32x32x16_bf16 v[34:49], v[230:233], v[114:117], v[34:49]
	v_mfma_f32_32x32x16_bf16 v[2:17], v[230:233], v[82:85], v[2:17]
	ds_read_b64_tr_b16 v[230:231], v225 offset:23040
	ds_read_b64_tr_b16 v[232:233], v225 offset:24192
	v_pk_add_f32 v[90:91], v[90:91], v[188:189] op_sel_hi:[1,0] neg_lo:[0,1] neg_hi:[0,1]
	v_pk_add_f32 v[92:93], v[92:93], v[188:189] op_sel_hi:[1,0] neg_lo:[0,1] neg_hi:[0,1]
	v_pk_add_f32 v[94:95], v[94:95], v[188:189] op_sel_hi:[1,0] neg_lo:[0,1] neg_hi:[0,1]
	v_pk_add_f32 v[96:97], v[96:97], v[188:189] op_sel_hi:[1,0] neg_lo:[0,1] neg_hi:[0,1]
	v_exp_f32_e32 v90, v90
	v_exp_f32_e32 v91, v91
	v_exp_f32_e32 v92, v92
	v_exp_f32_e32 v93, v93
	v_exp_f32_e32 v94, v94
	v_exp_f32_e32 v95, v95
	v_exp_f32_e32 v96, v96
	v_exp_f32_e32 v97, v97
	v_pk_add_f32 v[220:221], v[90:91], v[92:93]
	v_pk_add_f32 v[220:221], v[220:221], v[94:95]
	v_pk_add_f32 v[220:221], v[220:221], v[96:97]
	v_add_f32_e32 v220, v220, v221
	v_add_f32_e32 v199, v199, v220
	v_cvt_pk_bf16_f32 v90, v90, v91
	v_cvt_pk_bf16_f32 v91, v92, v93
	v_cvt_pk_bf16_f32 v92, v94, v95
	v_cvt_pk_bf16_f32 v93, v96, v97
	s_waitcnt lgkmcnt(4)
	v_mfma_f32_32x32x16_bf16 v[50:65], v[234:237], v[122:125], v[50:65]
	v_mfma_f32_32x32x16_bf16 v[18:33], v[234:237], v[90:93], v[18:33]
	ds_read_b64_tr_b16 v[234:235], v225 offset:23104
	ds_read_b64_tr_b16 v[236:237], v225 offset:24256
	v_pk_add_f32 v[98:99], v[98:99], v[186:187] op_sel_hi:[1,0] neg_lo:[0,1] neg_hi:[0,1]
	v_pk_add_f32 v[100:101], v[100:101], v[186:187] op_sel_hi:[1,0] neg_lo:[0,1] neg_hi:[0,1]
	v_pk_add_f32 v[102:103], v[102:103], v[186:187] op_sel_hi:[1,0] neg_lo:[0,1] neg_hi:[0,1]
	v_pk_add_f32 v[104:105], v[104:105], v[186:187] op_sel_hi:[1,0] neg_lo:[0,1] neg_hi:[0,1]
	v_exp_f32_e32 v98, v98
	v_exp_f32_e32 v99, v99
	v_exp_f32_e32 v100, v100
	v_exp_f32_e32 v101, v101
	v_exp_f32_e32 v102, v102
	v_exp_f32_e32 v103, v103
	v_exp_f32_e32 v104, v104
	v_exp_f32_e32 v105, v105
	v_pk_add_f32 v[220:221], v[98:99], v[100:101]
	v_pk_add_f32 v[220:221], v[220:221], v[102:103]
	v_pk_add_f32 v[220:221], v[220:221], v[104:105]
	v_add_f32_e32 v220, v220, v221
	v_add_f32_e32 v201, v201, v220
	v_cvt_pk_bf16_f32 v98, v98, v99
	v_cvt_pk_bf16_f32 v99, v100, v101
	v_cvt_pk_bf16_f32 v100, v102, v103
	v_cvt_pk_bf16_f32 v101, v104, v105
	s_waitcnt lgkmcnt(4)
	v_mfma_f32_32x32x16_bf16 v[34:49], v[226:229], v[122:125], v[34:49]
	v_mfma_f32_32x32x16_bf16 v[2:17], v[226:229], v[90:93], v[2:17]
	ds_read_b64_tr_b16 v[226:227], v225 offset:25344
	ds_read_b64_tr_b16 v[228:229], v225 offset:26496
	v_pk_add_f32 v[66:67], v[66:67], v[188:189] op_sel_hi:[1,0] neg_lo:[0,1] neg_hi:[0,1]
	v_pk_add_f32 v[68:69], v[68:69], v[188:189] op_sel_hi:[1,0] neg_lo:[0,1] neg_hi:[0,1]
	v_pk_add_f32 v[70:71], v[70:71], v[188:189] op_sel_hi:[1,0] neg_lo:[0,1] neg_hi:[0,1]
	v_pk_add_f32 v[72:73], v[72:73], v[188:189] op_sel_hi:[1,0] neg_lo:[0,1] neg_hi:[0,1]
	v_exp_f32_e32 v66, v66
	v_exp_f32_e32 v67, v67
	v_exp_f32_e32 v68, v68
	v_exp_f32_e32 v69, v69
	v_exp_f32_e32 v70, v70
	v_exp_f32_e32 v71, v71
	v_exp_f32_e32 v72, v72
	v_exp_f32_e32 v73, v73
	v_pk_add_f32 v[220:221], v[66:67], v[68:69]
	v_pk_add_f32 v[220:221], v[220:221], v[70:71]
	v_pk_add_f32 v[220:221], v[220:221], v[72:73]
	v_add_f32_e32 v220, v220, v221
	v_add_f32_e32 v199, v199, v220
	v_cvt_pk_bf16_f32 v66, v66, v67
	v_cvt_pk_bf16_f32 v67, v68, v69
	v_cvt_pk_bf16_f32 v68, v70, v71
	v_cvt_pk_bf16_f32 v69, v72, v73
	s_waitcnt lgkmcnt(4)
	v_mfma_f32_32x32x16_bf16 v[50:65], v[230:233], v[98:101], v[50:65]
	v_mfma_f32_32x32x16_bf16 v[18:33], v[230:233], v[66:69], v[18:33]
	ds_read_b64_tr_b16 v[230:231], v225 offset:25408
	ds_read_b64_tr_b16 v[232:233], v225 offset:26560
	v_pk_add_f32 v[106:107], v[106:107], v[186:187] op_sel_hi:[1,0] neg_lo:[0,1] neg_hi:[0,1]
	v_pk_add_f32 v[108:109], v[108:109], v[186:187] op_sel_hi:[1,0] neg_lo:[0,1] neg_hi:[0,1]
	v_pk_add_f32 v[110:111], v[110:111], v[186:187] op_sel_hi:[1,0] neg_lo:[0,1] neg_hi:[0,1]
	v_pk_add_f32 v[112:113], v[112:113], v[186:187] op_sel_hi:[1,0] neg_lo:[0,1] neg_hi:[0,1]
	v_exp_f32_e32 v106, v106
	v_exp_f32_e32 v107, v107
	v_exp_f32_e32 v108, v108
	v_exp_f32_e32 v109, v109
	v_exp_f32_e32 v110, v110
	v_exp_f32_e32 v111, v111
	v_exp_f32_e32 v112, v112
	v_exp_f32_e32 v113, v113
	v_pk_add_f32 v[220:221], v[106:107], v[108:109]
	v_pk_add_f32 v[220:221], v[220:221], v[110:111]
	v_pk_add_f32 v[220:221], v[220:221], v[112:113]
	v_add_f32_e32 v220, v220, v221
	v_add_f32_e32 v201, v201, v220
	v_cvt_pk_bf16_f32 v106, v106, v107
	v_cvt_pk_bf16_f32 v107, v108, v109
	v_cvt_pk_bf16_f32 v108, v110, v111
	v_cvt_pk_bf16_f32 v109, v112, v113
	s_waitcnt lgkmcnt(4)
	v_mfma_f32_32x32x16_bf16 v[34:49], v[234:237], v[98:101], v[34:49]
	v_mfma_f32_32x32x16_bf16 v[2:17], v[234:237], v[66:69], v[2:17]
	v_pk_add_f32 v[74:75], v[74:75], v[188:189] op_sel_hi:[1,0] neg_lo:[0,1] neg_hi:[0,1]
	v_pk_add_f32 v[76:77], v[76:77], v[188:189] op_sel_hi:[1,0] neg_lo:[0,1] neg_hi:[0,1]
	v_pk_add_f32 v[78:79], v[78:79], v[188:189] op_sel_hi:[1,0] neg_lo:[0,1] neg_hi:[0,1]
	v_pk_add_f32 v[80:81], v[80:81], v[188:189] op_sel_hi:[1,0] neg_lo:[0,1] neg_hi:[0,1]
	v_exp_f32_e32 v74, v74
	v_exp_f32_e32 v75, v75
	v_exp_f32_e32 v76, v76
	v_exp_f32_e32 v77, v77
	v_exp_f32_e32 v78, v78
	v_exp_f32_e32 v79, v79
	v_exp_f32_e32 v80, v80
	v_exp_f32_e32 v81, v81
	v_pk_add_f32 v[220:221], v[74:75], v[76:77]
	v_pk_add_f32 v[220:221], v[220:221], v[78:79]
	v_pk_add_f32 v[220:221], v[220:221], v[80:81]
	v_add_f32_e32 v220, v220, v221
	v_add_f32_e32 v199, v199, v220
	v_cvt_pk_bf16_f32 v74, v74, v75
	v_cvt_pk_bf16_f32 v75, v76, v77
	v_cvt_pk_bf16_f32 v76, v78, v79
	v_cvt_pk_bf16_f32 v77, v80, v81
	s_waitcnt lgkmcnt(2)
	v_mfma_f32_32x32x16_bf16 v[50:65], v[226:229], v[106:109], v[50:65]
	v_mfma_f32_32x32x16_bf16 v[18:33], v[226:229], v[74:77], v[18:33]
	s_waitcnt lgkmcnt(0)
	v_mfma_f32_32x32x16_bf16 v[34:49], v[230:233], v[106:109], v[34:49]
	v_mfma_f32_32x32x16_bf16 v[2:17], v[230:233], v[74:77], v[2:17]

.LBB0_378:
	v_or_b32_e32 v221, s35, v215
	v_mad_u32_u24 v225, v221, s89, v224
	ds_read_b64_tr_b16 v[226:227], v225 offset:18432
	ds_read_b64_tr_b16 v[228:229], v225 offset:19584
	ds_read_b64_tr_b16 v[230:231], v225 offset:18496
	ds_read_b64_tr_b16 v[232:233], v225 offset:19648
	ds_read_b64_tr_b16 v[234:235], v225 offset:20736
	ds_read_b64_tr_b16 v[236:237], v225 offset:21888
	v_pk_add_f32 v[128:129], v[128:129], v[200:201] op_sel_hi:[1,0] neg_lo:[0,1] neg_hi:[0,1]
	v_pk_add_f32 v[130:131], v[130:131], v[200:201] op_sel_hi:[1,0] neg_lo:[0,1] neg_hi:[0,1]
	v_pk_add_f32 v[132:133], v[132:133], v[200:201] op_sel_hi:[1,0] neg_lo:[0,1] neg_hi:[0,1]
	v_pk_add_f32 v[134:135], v[134:135], v[200:201] op_sel_hi:[1,0] neg_lo:[0,1] neg_hi:[0,1]
	v_exp_f32_e32 v128, v128
	v_exp_f32_e32 v129, v129
	v_exp_f32_e32 v130, v130
	v_exp_f32_e32 v131, v131
	v_exp_f32_e32 v132, v132
	v_exp_f32_e32 v133, v133
	v_exp_f32_e32 v134, v134
	v_exp_f32_e32 v135, v135
	v_pk_add_f32 v[220:221], v[128:129], v[130:131]
	v_pk_add_f32 v[220:221], v[220:221], v[132:133]
	v_pk_add_f32 v[220:221], v[220:221], v[134:135]
	v_add_f32_e32 v220, v220, v221
	v_add_f32_e32 v216, v216, v220
	v_cvt_pk_bf16_f32 v128, v128, v129
	v_cvt_pk_bf16_f32 v129, v130, v131
	v_cvt_pk_bf16_f32 v130, v132, v133
	v_cvt_pk_bf16_f32 v131, v134, v135
	v_pk_add_f32 v[80:81], v[80:81], v[202:203] op_sel_hi:[1,0] neg_lo:[0,1] neg_hi:[0,1]
	v_pk_add_f32 v[82:83], v[82:83], v[202:203] op_sel_hi:[1,0] neg_lo:[0,1] neg_hi:[0,1]
	v_pk_add_f32 v[84:85], v[84:85], v[202:203] op_sel_hi:[1,0] neg_lo:[0,1] neg_hi:[0,1]
	v_pk_add_f32 v[86:87], v[86:87], v[202:203] op_sel_hi:[1,0] neg_lo:[0,1] neg_hi:[0,1]
	v_exp_f32_e32 v80, v80
	v_exp_f32_e32 v81, v81
	v_exp_f32_e32 v82, v82
	v_exp_f32_e32 v83, v83
	v_exp_f32_e32 v84, v84
	v_exp_f32_e32 v85, v85
	v_exp_f32_e32 v86, v86
	v_exp_f32_e32 v87, v87
	v_pk_add_f32 v[220:221], v[80:81], v[82:83]
	v_pk_add_f32 v[220:221], v[220:221], v[84:85]
	v_pk_add_f32 v[220:221], v[220:221], v[86:87]
	v_add_f32_e32 v220, v220, v221
	v_add_f32_e32 v212, v212, v220
	v_cvt_pk_bf16_f32 v80, v80, v81
	v_cvt_pk_bf16_f32 v81, v82, v83
	v_cvt_pk_bf16_f32 v82, v84, v85
	v_cvt_pk_bf16_f32 v83, v86, v87
	s_waitcnt lgkmcnt(4)
	v_mfma_f32_32x32x16_bf16 v[64:79], v[226:229], v[128:131], v[64:79]
	v_mfma_f32_32x32x16_bf16 v[32:47], v[226:229], v[80:83], v[32:47]
	ds_read_b64_tr_b16 v[226:227], v225 offset:20800
	ds_read_b64_tr_b16 v[228:229], v225 offset:21952
	v_pk_add_f32 v[136:137], v[136:137], v[200:201] op_sel_hi:[1,0] neg_lo:[0,1] neg_hi:[0,1]
	v_pk_add_f32 v[138:139], v[138:139], v[200:201] op_sel_hi:[1,0] neg_lo:[0,1] neg_hi:[0,1]
	v_pk_add_f32 v[140:141], v[140:141], v[200:201] op_sel_hi:[1,0] neg_lo:[0,1] neg_hi:[0,1]
	v_pk_add_f32 v[142:143], v[142:143], v[200:201] op_sel_hi:[1,0] neg_lo:[0,1] neg_hi:[0,1]
	v_exp_f32_e32 v136, v136
	v_exp_f32_e32 v137, v137
	v_exp_f32_e32 v138, v138
	v_exp_f32_e32 v139, v139
	v_exp_f32_e32 v140, v140
	v_exp_f32_e32 v141, v141
	v_exp_f32_e32 v142, v142
	v_exp_f32_e32 v143, v143
	v_pk_add_f32 v[220:221], v[136:137], v[138:139]
	v_pk_add_f32 v[220:221], v[220:221], v[140:141]
	v_pk_add_f32 v[220:221], v[220:221], v[142:143]
	v_add_f32_e32 v220, v220, v221
	v_add_f32_e32 v216, v216, v220
	v_cvt_pk_bf16_f32 v136, v136, v137
	v_cvt_pk_bf16_f32 v137, v138, v139
	v_cvt_pk_bf16_f32 v138, v140, v141
	v_cvt_pk_bf16_f32 v139, v142, v143
	s_waitcnt lgkmcnt(4)
	v_mfma_f32_32x32x16_bf16 v[48:63], v[230:233], v[128:131], v[48:63]
	v_mfma_f32_32x32x16_bf16 v[16:31], v[230:233], v[80:83], v[16:31]
	ds_read_b64_tr_b16 v[230:231], v225 offset:23040
	ds_read_b64_tr_b16 v[232:233], v225 offset:24192
	v_pk_add_f32 v[88:89], v[88:89], v[202:203] op_sel_hi:[1,0] neg_lo:[0,1] neg_hi:[0,1]
	v_pk_add_f32 v[90:91], v[90:91], v[202:203] op_sel_hi:[1,0] neg_lo:[0,1] neg_hi:[0,1]
	v_pk_add_f32 v[92:93], v[92:93], v[202:203] op_sel_hi:[1,0] neg_lo:[0,1] neg_hi:[0,1]
	v_pk_add_f32 v[94:95], v[94:95], v[202:203] op_sel_hi:[1,0] neg_lo:[0,1] neg_hi:[0,1]
	v_exp_f32_e32 v88, v88
	v_exp_f32_e32 v89, v89
	v_exp_f32_e32 v90, v90
	v_exp_f32_e32 v91, v91
	v_exp_f32_e32 v92, v92
	v_exp_f32_e32 v93, v93
	v_exp_f32_e32 v94, v94
	v_exp_f32_e32 v95, v95
	v_pk_add_f32 v[220:221], v[88:89], v[90:91]
	v_pk_add_f32 v[220:221], v[220:221], v[92:93]
	v_pk_add_f32 v[220:221], v[220:221], v[94:95]
	v_add_f32_e32 v220, v220, v221
	v_add_f32_e32 v212, v212, v220
	v_cvt_pk_bf16_f32 v88, v88, v89
	v_cvt_pk_bf16_f32 v89, v90, v91
	v_cvt_pk_bf16_f32 v90, v92, v93
	v_cvt_pk_bf16_f32 v91, v94, v95
	s_waitcnt lgkmcnt(4)
	v_mfma_f32_32x32x16_bf16 v[64:79], v[234:237], v[136:139], v[64:79]
	v_mfma_f32_32x32x16_bf16 v[32:47], v[234:237], v[88:91], v[32:47]
	ds_read_b64_tr_b16 v[234:235], v225 offset:23104
	ds_read_b64_tr_b16 v[236:237], v225 offset:24256
	v_pk_add_f32 v[112:113], v[112:113], v[200:201] op_sel_hi:[1,0] neg_lo:[0,1] neg_hi:[0,1]
	v_pk_add_f32 v[114:115], v[114:115], v[200:201] op_sel_hi:[1,0] neg_lo:[0,1] neg_hi:[0,1]
	v_pk_add_f32 v[116:117], v[116:117], v[200:201] op_sel_hi:[1,0] neg_lo:[0,1] neg_hi:[0,1]
	v_pk_add_f32 v[118:119], v[118:119], v[200:201] op_sel_hi:[1,0] neg_lo:[0,1] neg_hi:[0,1]
	v_exp_f32_e32 v112, v112
	v_exp_f32_e32 v113, v113
	v_exp_f32_e32 v114, v114
	v_exp_f32_e32 v115, v115
	v_exp_f32_e32 v116, v116
	v_exp_f32_e32 v117, v117
	v_exp_f32_e32 v118, v118
	v_exp_f32_e32 v119, v119
	v_pk_add_f32 v[220:221], v[112:113], v[114:115]
	v_pk_add_f32 v[220:221], v[220:221], v[116:117]
	v_pk_add_f32 v[220:221], v[220:221], v[118:119]
	v_add_f32_e32 v220, v220, v221
	v_add_f32_e32 v216, v216, v220
	v_cvt_pk_bf16_f32 v112, v112, v113
	v_cvt_pk_bf16_f32 v113, v114, v115
	v_cvt_pk_bf16_f32 v114, v116, v117
	v_cvt_pk_bf16_f32 v115, v118, v119
	s_waitcnt lgkmcnt(4)
	v_mfma_f32_32x32x16_bf16 v[48:63], v[226:229], v[136:139], v[48:63]
	v_mfma_f32_32x32x16_bf16 v[16:31], v[226:229], v[88:91], v[16:31]
	ds_read_b64_tr_b16 v[226:227], v225 offset:25344
	ds_read_b64_tr_b16 v[228:229], v225 offset:26496
	v_pk_add_f32 v[96:97], v[96:97], v[202:203] op_sel_hi:[1,0] neg_lo:[0,1] neg_hi:[0,1]
	v_pk_add_f32 v[98:99], v[98:99], v[202:203] op_sel_hi:[1,0] neg_lo:[0,1] neg_hi:[0,1]
	v_pk_add_f32 v[100:101], v[100:101], v[202:203] op_sel_hi:[1,0] neg_lo:[0,1] neg_hi:[0,1]
	v_pk_add_f32 v[102:103], v[102:103], v[202:203] op_sel_hi:[1,0] neg_lo:[0,1] neg_hi:[0,1]
	v_exp_f32_e32 v96, v96
	v_exp_f32_e32 v97, v97
	v_exp_f32_e32 v98, v98
	v_exp_f32_e32 v99, v99
	v_exp_f32_e32 v100, v100
	v_exp_f32_e32 v101, v101
	v_exp_f32_e32 v102, v102
	v_exp_f32_e32 v103, v103
	v_pk_add_f32 v[220:221], v[96:97], v[98:99]
	v_pk_add_f32 v[220:221], v[220:221], v[100:101]
	v_pk_add_f32 v[220:221], v[220:221], v[102:103]
	v_add_f32_e32 v220, v220, v221
	v_add_f32_e32 v212, v212, v220
	v_cvt_pk_bf16_f32 v96, v96, v97
	v_cvt_pk_bf16_f32 v97, v98, v99
	v_cvt_pk_bf16_f32 v98, v100, v101
	v_cvt_pk_bf16_f32 v99, v102, v103
	s_waitcnt lgkmcnt(4)
	v_mfma_f32_32x32x16_bf16 v[64:79], v[230:233], v[112:115], v[64:79]
	v_mfma_f32_32x32x16_bf16 v[32:47], v[230:233], v[96:99], v[32:47]
	ds_read_b64_tr_b16 v[230:231], v225 offset:25408
	ds_read_b64_tr_b16 v[232:233], v225 offset:26560
	v_pk_add_f32 v[120:121], v[120:121], v[200:201] op_sel_hi:[1,0] neg_lo:[0,1] neg_hi:[0,1]
	v_pk_add_f32 v[122:123], v[122:123], v[200:201] op_sel_hi:[1,0] neg_lo:[0,1] neg_hi:[0,1]
	v_pk_add_f32 v[124:125], v[124:125], v[200:201] op_sel_hi:[1,0] neg_lo:[0,1] neg_hi:[0,1]
	v_pk_add_f32 v[126:127], v[126:127], v[200:201] op_sel_hi:[1,0] neg_lo:[0,1] neg_hi:[0,1]
	v_exp_f32_e32 v120, v120
	v_exp_f32_e32 v121, v121
	v_exp_f32_e32 v122, v122
	v_exp_f32_e32 v123, v123
	v_exp_f32_e32 v124, v124
	v_exp_f32_e32 v125, v125
	v_exp_f32_e32 v126, v126
	v_exp_f32_e32 v127, v127
	v_pk_add_f32 v[220:221], v[120:121], v[122:123]
	v_pk_add_f32 v[220:221], v[220:221], v[124:125]
	v_pk_add_f32 v[220:221], v[220:221], v[126:127]
	v_add_f32_e32 v220, v220, v221
	v_add_f32_e32 v216, v216, v220
	v_cvt_pk_bf16_f32 v120, v120, v121
	v_cvt_pk_bf16_f32 v121, v122, v123
	v_cvt_pk_bf16_f32 v122, v124, v125
	v_cvt_pk_bf16_f32 v123, v126, v127
	s_waitcnt lgkmcnt(4)
	v_mfma_f32_32x32x16_bf16 v[48:63], v[234:237], v[112:115], v[48:63]
	v_mfma_f32_32x32x16_bf16 v[16:31], v[234:237], v[96:99], v[16:31]
	v_pk_add_f32 v[104:105], v[104:105], v[202:203] op_sel_hi:[1,0] neg_lo:[0,1] neg_hi:[0,1]
	v_pk_add_f32 v[106:107], v[106:107], v[202:203] op_sel_hi:[1,0] neg_lo:[0,1] neg_hi:[0,1]
	v_pk_add_f32 v[108:109], v[108:109], v[202:203] op_sel_hi:[1,0] neg_lo:[0,1] neg_hi:[0,1]
	v_pk_add_f32 v[110:111], v[110:111], v[202:203] op_sel_hi:[1,0] neg_lo:[0,1] neg_hi:[0,1]
	v_exp_f32_e32 v104, v104
	v_exp_f32_e32 v105, v105
	v_exp_f32_e32 v106, v106
	v_exp_f32_e32 v107, v107
	v_exp_f32_e32 v108, v108
	v_exp_f32_e32 v109, v109
	v_exp_f32_e32 v110, v110
	v_exp_f32_e32 v111, v111
	v_pk_add_f32 v[220:221], v[104:105], v[106:107]
	v_pk_add_f32 v[220:221], v[220:221], v[108:109]
	v_pk_add_f32 v[220:221], v[220:221], v[110:111]
	v_add_f32_e32 v220, v220, v221
	v_add_f32_e32 v212, v212, v220
	v_cvt_pk_bf16_f32 v104, v104, v105
	v_cvt_pk_bf16_f32 v105, v106, v107
	v_cvt_pk_bf16_f32 v106, v108, v109
	v_cvt_pk_bf16_f32 v107, v110, v111
	s_waitcnt lgkmcnt(2)
	v_mfma_f32_32x32x16_bf16 v[64:79], v[226:229], v[120:123], v[64:79]
	v_mfma_f32_32x32x16_bf16 v[32:47], v[226:229], v[104:107], v[32:47]
	s_waitcnt lgkmcnt(0)
	v_mfma_f32_32x32x16_bf16 v[48:63], v[230:233], v[120:123], v[48:63]
	v_mfma_f32_32x32x16_bf16 v[16:31], v[230:233], v[104:107], v[16:31]
